# P8 work queues: popping thread also reads all 8 queue counters in the same round trip and broadcasts an exhausted-queue mask; exhausted queues are skipped without an atomic probe and two workgroup bar
# baseline (speedup 1.0000x reference)
.LBB0_934:
	s_cmp_lt_i32 s4, 9
	s_cselect_b64 s[0:1], -1, 0
	s_cmp_gt_i32 s5, 8
	s_cselect_b64 s[2:3], -1, 0
	s_and_b64 s[0:1], s[0:1], s[2:3]
	s_andn2_b64 vcc, exec, s[0:1]
	v_mbcnt_lo_u32_b32 v200, -1, 0
	s_cbranch_vccnz .LBB0_1106
	v_readlane_b32 s0, v252, 7
	v_mbcnt_lo_u32_b32 v202, -1, 0
	v_mbcnt_hi_u32_b32 v202, -1, v202
	s_movk_i32 s2, 0xc00
	s_add_u32 s36, s90, 0x2000
	v_add_u32_e32 v201, s0, v202
	s_waitcnt vmcnt(0)
	v_ashrrev_i32_e32 v0, 3, v201
	v_mul_lo_u32 v1, v0, s2
	v_ashrrev_i32_e32 v205, 2, v201
	s_movk_i32 s2, 0x90
	s_addc_u32 s37, s91, 0
	s_lshr_b32 s40, s18, 7
	v_and_b32_e32 v2, 7, v202
	v_mul_lo_u32 v4, v205, s2
	s_movk_i32 s2, 0x190
	s_add_i32 s40, s40, 1
	v_and_b32_e32 v203, 31, v202
	v_lshl_or_b32 v188, v2, 3, v1
	v_lshlrev_b32_e32 v1, 4, v2
	v_and_b32_e32 v2, 3, v202
	v_mul_lo_u32 v6, v0, s2
	v_readlane_b32 s2, v252, 6
	v_mov_b32_e32 v0, 0
	s_cmpk_lt_u32 s18, 0x80
	v_lshlrev_b32_e32 v206, 3, v2
	v_lshlrev_b32_e32 v5, 4, v2
	v_ashrrev_i32_e32 v7, 5, v202
	v_lshl_or_b32 v2, s2, 5, v203
	v_mov_b32_e32 v3, v0
	s_movk_i32 s2, 0x1800
	s_cselect_b32 s41, 33, 0
	v_ashrrev_i32_e32 v189, 31, v188
	v_mad_u64_u32 v[190:191], s[4:5], v2, s2, 0
	v_lshlrev_b32_e32 v186, 3, v7
	v_lshlrev_b64 v[192:193], 13, v[2:3]
	v_lshlrev_b32_e32 v184, 2, v7
	v_mov_b64_e32 v[2:3], 0x60000
	s_add_i32 s42, 0, 0x20140
	s_getreg_b32 s33, hwreg(HW_REG_XCC_ID, 0, 4)
	s_mov_b32 s3, 0
	v_cmp_eq_u32_e64 s[0:1], 0, v201
	v_ashrrev_i32_e32 v187, 31, v186
	v_add3_u32 v207, 0, v6, v1
	v_add3_u32 v208, 0, v4, v5
	v_mul_u32_u24_e32 v209, 0x190, v203
	v_lshlrev_b32_e32 v204, 4, v7
	v_mul_u32_u24_e32 v210, 0x90, v203
	v_ashrrev_i32_e32 v185, 31, v184
	s_mov_b64 s[4:5], 0x60000
	v_lshl_add_u64 v[194:195], v[188:189], 1, v[2:3]
	v_mov_b32_e32 v211, s42
	s_mov_b64 s[6:7], 0x80
	s_mov_b32 s43, 0x41000000
	v_mbcnt_hi_u32_b32 v212, -1, v200
	s_mov_b32 s44, 0
	s_mov_b32 s101, 0
	s_branch .LBB0_937

.LBB0_937:
	s_add_i32 s2, s44, s33
	s_and_b32 s45, s2, 7
	s_bitcmp1_b32 s101, s45
	s_cbranch_scc1 .LBB0_936
	s_lshl_b32 s2, s45, 8
	s_add_u32 s8, s36, s2
	s_addc_u32 s9, s37, 0
	s_branch .LBB0_940

.LBB0_943:
	s_or_b64 exec, exec, s[28:29]
	global_load_dword v3, v0, s[36:37] sc0 sc1
	global_load_dword v4, v0, s[36:37] offset:256 sc0 sc1
	global_load_dword v5, v0, s[36:37] offset:512 sc0 sc1
	global_load_dword v6, v0, s[36:37] offset:768 sc0 sc1
	global_load_dword v7, v0, s[36:37] offset:1024 sc0 sc1
	global_load_dword v8, v0, s[36:37] offset:1280 sc0 sc1
	global_load_dword v9, v0, s[36:37] offset:1536 sc0 sc1
	global_load_dword v10, v0, s[36:37] offset:1792 sc0 sc1
	s_waitcnt vmcnt(0)
	v_readfirstlane_b32 s2, v2
	s_mov_b32 s99, 0
	v_readfirstlane_b32 s100, v3
	s_cmpk_gt_u32 s100, 0x4f
	s_cselect_b32 s100, 0x10000, 0
	s_or_b32 s99, s99, s100
	v_readfirstlane_b32 s100, v4
	s_cmpk_gt_u32 s100, 0x4f
	s_cselect_b32 s100, 0x20000, 0
	s_or_b32 s99, s99, s100
	v_readfirstlane_b32 s100, v5
	s_cmpk_gt_u32 s100, 0x4f
	s_cselect_b32 s100, 0x40000, 0
	s_or_b32 s99, s99, s100
	v_readfirstlane_b32 s100, v6
	s_cmpk_gt_u32 s100, 0x4f
	s_cselect_b32 s100, 0x80000, 0
	s_or_b32 s99, s99, s100
	v_readfirstlane_b32 s100, v7
	s_cmpk_gt_u32 s100, 0x4f
	s_cselect_b32 s100, 0x100000, 0
	s_or_b32 s99, s99, s100
	v_readfirstlane_b32 s100, v8
	s_cmpk_gt_u32 s100, 0x4f
	s_cselect_b32 s100, 0x200000, 0
	s_or_b32 s99, s99, s100
	v_readfirstlane_b32 s100, v9
	s_cmpk_gt_u32 s100, 0x4f
	s_cselect_b32 s100, 0x400000, 0
	s_or_b32 s99, s99, s100
	v_readfirstlane_b32 s100, v10
	s_cmpk_gt_u32 s100, 0x4f
	s_cselect_b32 s100, 0x800000, 0
	s_or_b32 s99, s99, s100
	v_mov_b32_e32 v2, s42
	s_nop 0
	v_add_u32_e32 v1, s2, v1
	v_or_b32_e32 v1, s99, v1
	ds_write_b32 v2, v1
.LBB0_944:
	s_or_b64 exec, exec, s[14:15]
	s_waitcnt lgkmcnt(0)
	s_waitcnt lgkmcnt(0)
	s_barrier
	ds_read_b32 v1, v211
	s_mov_b64 s[14:15], -1
	s_waitcnt lgkmcnt(0)
	s_barrier
	v_readfirstlane_b32 s2, v1
	s_lshr_b32 s100, s2, 16
	s_or_b32 s101, s101, s100
	s_and_b32 s2, s2, 0xffff
	s_cmpk_gt_i32 s2, 0x4f
	s_cbranch_scc1 .LBB0_939
	s_lshl_b32 s47, s2, 3
	s_and_b32 s2, s2, 0x1ffffff0
	s_cmp_lg_u32 s2, 48
	s_mov_b64 s[38:39], -1
	s_cbranch_scc0 .LBB0_947
	s_or_b32 s2, s47, s45
	s_add_i32 s14, s2, 0xffffff80
	s_cmpk_lt_i32 s2, 0x180
	s_cselect_b32 s2, s2, s14
	s_ashr_i32 s14, s2, 4
	s_sub_i32 s38, 31, s14
	s_lshl_b32 s14, s38, 8
	s_and_b32 s2, s2, 15
	s_ashr_i32 s15, s14, 31
	s_mul_i32 s28, s38, 0x180000
	s_mul_hi_i32 s29, s14, 0x1800
	s_add_u32 s28, s10, s28
	s_addc_u32 s29, s11, s29
	s_mul_i32 s30, s2, 0x180
	s_add_u32 s34, s28, s30
	s_addc_u32 s35, s29, 0
	s_add_u32 s30, s84, s30
	s_addc_u32 s31, s85, 0
	s_lshl_b32 s28, s2, 21
	s_add_u32 s28, s16, s28
	s_addc_u32 s29, s17, 0
	s_lshl_b64 s[14:15], s[14:15], 13
	s_add_u32 s14, s12, s14
	s_addc_u32 s15, s13, s15
	s_lshl_b32 s2, s2, 8
	s_add_u32 s2, s14, s2
	s_addc_u32 s15, s15, 0
	s_add_u32 s14, s2, 0x1000
	s_addc_u32 s15, s15, 0
	s_lshl_b32 s38, s38, 2
	s_add_i32 s2, s38, 4
	s_add_i32 s46, s40, s38
	s_mov_b64 s[38:39], 0
